# P2x scan loop: one static s_setprio 2 for the use_v waves (0-3), which carry the extra Kt/V MFMAs and are what the barriers wait for; reset behind the item loop
# speedup vs baseline: 1.0042x; 1.0042x over previous
.LBB0_554:
	s_waitcnt vmcnt(1)
	v_lshlrev_b32_e32 v0, 16, v75
	v_readlane_b32 s0, v248, 2
	v_cndmask_b32_e64 v0, 0, v0, s[8:9]
	v_add_u32_e32 v137, s78, v162
	v_lshlrev_b32_e32 v1, 16, v81
	v_add_u32_e32 v139, s0, v162
	s_add_i32 s0, s70, s41
	s_mul_i32 s40, s40, 7
	ds_write_b32 v137, v0 offset:13824
	v_add_f32_e32 v0, 0, v0
	v_cndmask_b32_e64 v1, 0, v1, s[8:9]
	s_sub_i32 s0, s0, s40
	v_add_f32_e32 v0, v0, v1
	s_lshl_b32 s0, s0, 8
	ds_write_b32 v139, v1 offset:13824
	ds_write_b32 v163, v0 offset:22016
	s_add_i32 s72, s48, s0
	v_mov_b32_e32 v12, v91
	v_mov_b32_e32 v13, v109
	v_mov_b32_e32 v14, v111
	v_mov_b32_e32 v15, v113
	v_mov_b32_e32 v8, v115
	v_mov_b32_e32 v9, v117
	v_mov_b32_e32 v10, v119
	v_mov_b32_e32 v11, v122
	v_mov_b32_e32 v4, v123
	v_mov_b32_e32 v5, v124
	v_mov_b32_e32 v6, v125
	v_mov_b32_e32 v7, v126
	v_mov_b32_e32 v0, v127
	v_mov_b32_e32 v1, v129
	v_mov_b32_e32 v2, v130
	v_mov_b32_e32 v3, v131
	s_waitcnt vmcnt(0)
	s_cmp_eq_u64 s[6:7], 0
	s_cbranch_scc1 .Lprio_skip
	s_setprio 2
.Lprio_skip:
	s_branch .LBB0_556
.LBB0_555:
	s_andn2_b64 vcc, exec, s[0:1]
	s_cbranch_vccz .LBB0_533

.LBB0_614:
	s_setprio 0
	s_and_b32 s0, 0xffff, s33
	s_cmp_lg_u32 s0, 0
	s_cselect_b64 s[0:1], -1, 0
	s_cmp_lg_u64 s[0:1], 0
	v_readlane_b32 s0, v250, 0
	v_readlane_b32 s1, v250, 1
	s_load_dword s0, s[0:1], 0x0
	v_writelane_b32 v248, s78, 5
	v_mov_b32_e32 v183, v47
	s_waitcnt lgkmcnt(0)
	s_addc_u32 s0, s0, 0
	s_cmpk_lg_i32 s0, 0x100
	s_cselect_b64 s[0:1], -1, 0
	s_sub_u32 s2, s74, 0x80
	s_cmpk_lt_u32 s2, 0x40
	s_cselect_b64 s[2:3], -1, 0
	s_or_b64 s[0:1], s[2:3], s[0:1]
	s_cmpk_gt_i32 s74, 0x2bf
	s_cselect_b64 s[2:3], -1, 0
	s_lshr_b32 s33, s79, 8
	v_writelane_b32 v248, s33, 6
	s_mulk_i32 s33, 0x6800
	s_add_i32 s33, s33, 0
	s_lshl_b32 s38, s44, 2
	s_cmp_eq_u32 s44, 0
	s_cselect_b64 s[84:85], -1, 0
	s_cmp_lg_u32 s44, 0
	s_cselect_b64 s[40:41], -1, 0
	s_cmp_eq_u32 s44, 1
	v_writelane_b32 v249, s40, 60
	s_cselect_b64 s[72:73], -1, 0
	s_cmp_lt_u32 s44, 2
	v_writelane_b32 v249, s41, 61
	s_cselect_b64 s[40:41], -1, 0
	v_writelane_b32 v248, s40, 7
	s_or_b32 s42, s38, 1
	v_writelane_b32 v249, s38, 58
	v_writelane_b32 v248, s41, 8
	s_lshl_b32 s38, s44, 10
	s_lshl_b32 s39, s42, 8
	v_writelane_b32 v248, s39, 9
	s_or_b32 s39, s38, 0x200
	v_writelane_b32 v248, s39, 10
	v_writelane_b32 v249, s38, 62
	s_or_b32 s38, s38, 0x300
	v_writelane_b32 v248, s38, 11
	s_lshl_b32 s38, s44, 8
	s_add_i32 s38, s33, s38
	s_cmp_eq_u32 s44, 3
	v_add_u32_e32 v67, s38, v50
	s_cselect_b64 s[38:39], -1, 0
	s_add_i32 s45, s45, s33
	v_mov_b32_e32 v0, s33
	s_movk_i32 s40, 0x90
	s_cmp_gt_u32 s44, 1
	s_mulk_i32 s44, 0x120
	v_mad_u32_u24 v2, v179, s40, v0
	v_add_u32_e32 v0, s44, v158
	s_mulk_i32 s42, 0x48
	s_cselect_b64 s[40:41], -1, 0
	v_lshl_add_u32 v71, v0, 1, s33
	v_add_u32_e32 v0, s42, v158
	s_add_i32 s43, s42, 0x48
	v_add3_u32 v69, s45, v166, v44
	v_lshl_add_u32 v73, v0, 1, s33
	v_add_u32_e32 v0, s43, v158
	s_addk_i32 s42, 0x90
	v_readlane_b32 s44, v250, 7
	v_lshl_add_u32 v75, v0, 1, s33
	v_add_u32_e32 v0, s42, v158
	v_cmp_gt_u32_e64 s[42:43], 32, v158
	v_readlane_b32 s52, v250, 15
	v_readlane_b32 s53, v250, 16
	v_readlane_b32 s54, v250, 17
	v_readlane_b32 s55, v250, 18
	v_readlane_b32 s56, v250, 19
	v_readlane_b32 s57, v250, 20
	v_readlane_b32 s58, v250, 21
	v_readlane_b32 s59, v250, 22
	v_writelane_b32 v248, s42, 12
	v_readlane_b32 s52, v250, 60
	v_readlane_b32 s66, v249, 10
	v_writelane_b32 v248, s43, 13
	v_readlane_b32 s45, v250, 8
	v_readlane_b32 s67, v249, 11
	s_add_u32 s44, s66, 0x2200000
	v_readlane_b32 s42, v248, 4
	s_addc_u32 s45, s67, 0
	s_lshl_b32 s42, s42, 1
	s_add_u32 s42, s44, s42
	v_lshl_add_u32 v77, v0, 1, s33
	v_lshlrev_b32_e32 v0, 1, v45
	v_readlane_b32 s60, v249, 4
	v_readlane_b32 s61, v249, 5
	v_writelane_b32 v248, s44, 14
	s_addc_u32 s43, s45, 0
	v_mov_b32_e32 v45, v47
	v_add3_u32 v79, s33, v0, v44
	v_readlane_b32 s50, v250, 13
	v_readlane_b32 s51, v250, 14
	v_lshl_add_u64 v[60:61], s[42:43], 0, v[44:45]
	v_lshl_add_u64 v[0:1], s[66:67], 0, v[182:183]
	s_mov_b64 s[42:43], 0x4746000
	s_or_b64 s[0:1], s[2:3], s[0:1]
	v_readlane_b32 s60, v249, 16
	v_add_u32_e32 v65, s33, v50
	v_lshl_add_u32 v81, v179, 2, s33
	v_lshl_add_u64 v[58:59], s[50:51], 0, v[182:183]
	v_lshl_add_u64 v[62:63], v[0:1], 0, s[42:43]
	s_and_b64 vcc, exec, s[0:1]
	v_add_u32_e32 v83, v2, v159
	v_cndmask_b32_e64 v85, 0, 1, s[72:73]
	v_readlane_b32 s61, v249, 17
	v_readlane_b32 s46, v250, 9
	v_readlane_b32 s47, v250, 10
	v_readlane_b32 s48, v250, 11
	v_readlane_b32 s49, v250, 12
	v_readlane_b32 s53, v250, 61
	v_readlane_b32 s54, v250, 62
	v_readlane_b32 s55, v250, 63
	v_readlane_b32 s56, v249, 0
	v_readlane_b32 s57, v249, 1
	v_readlane_b32 s58, v249, 2
	v_readlane_b32 s59, v249, 3
	v_readlane_b32 s62, v249, 6
	v_readlane_b32 s63, v249, 7
	v_readlane_b32 s64, v249, 8
	v_readlane_b32 s65, v249, 9
	v_writelane_b32 v248, s45, 15
	s_cbranch_vccnz .LBB0_648
	v_readlane_b32 s0, v249, 45
	s_mov_b32 s0, s74
	s_cmpk_lt_u32 s0, 0x80
	s_cselect_b32 s1, 0x240, 0
	s_add_i32 s0, s0, s1
	s_add_i32 s42, s0, 0xffffff00
	s_lshl_b32 s0, s0, 1
	v_readlane_b32 s1, v248, 6
	s_add_i32 s0, s1, s0
	s_add_i32 s43, s0, 0xfffffe80
	v_mov_b32_e32 v21, 0
	s_lshl_b32 s74, s43, 6
	s_mov_b32 s79, 0
	s_mov_b32 s80, 0xf800000
	v_mov_b32_e32 v40, 0x260
	s_movk_i32 s81, 0x7fff
	v_mov_b32_e32 v41, 0xe00
	s_branch .LBB0_617
